# adds: EpiRes second-half residual prefetch for the GLA-out GEMM; GLA scan gate log-sigmoid computed stage-wise over the 16 rows (no per-element dependent chains)
# baseline (speedup 1.0000x reference)
; __device__ __forceinline__ void gla_scan_phase2(LAS unsigned char* lds, const bf16_t* proj, const float* gbuf, const float* wgu  , const float* bg  ,
;                                                 bf16_t* ob0, bf16_t* ob1) {
;     ...
;                 if (n < NCH) {
;                     const int tok0 = b * SEQ + (dir ? NCH - 1 - n : n) * CH;
;                     LAS unsigned char* set = lds + (n & 1) * G2_SET;
;                     const f32x4 ga = gna, gb = gnb;
;                     const unsigned srow = (unsigned)tok0 * (unsigned)(GINP * 2);
;                     unsigned short qv[16], kv[16];
; #pragma unroll
;                     for (int ii = 0; ii < 16; ++ii) { qv[ii] = __builtin_amdgcn_raw_buffer_load_b16(prs, qvoff, srow + (unsigned)(ii * GINP * 2), 0);
;                                                        kv[ii] = __builtin_amdgcn_raw_buffer_load_b16(prs, qvoff + 1024u, srow + (unsigned)(ii * GINP * 2), 0); }
;                     unsigned vw[16];
; #pragma unroll
;                     for (int ii = 0; ii < 16; ++ii) vw[ii] = __builtin_amdgcn_raw_buffer_load_b32(prs, vvoff, srow + (unsigned)(ii * GINP * 2), 0);
;                     { const int n1 = n + 1 < NCH ? n + 1 : n; const float* grow = gbuf + (size_t)(b * SEQ + (dir ? NCH - 1 - n1 : n1) * CH + r) * 32 + dir * 16 + 8 * hh;
;                       gna = *(const f32x4*)grow; gnb = *(const f32x4*)(grow + 4); }
;                     {
;                         u32x4 ah, al;
;                         ah.x = pk2(ga[0], ga[1]); ah.y = pk2(ga[2], ga[3]); ah.z = pk2(gb[0], gb[1]); ah.w = pk2(gb[2], gb[3]);
;                         al.x = pk2(ga[0] - bflo(ah.x), ga[1] - bfhi(ah.x)); al.y = pk2(ga[2] - bflo(ah.y), ga[3] - bfhi(ah.y));
;                         al.z = pk2(gb[0] - bflo(ah.z), gb[1] - bfhi(ah.z)); al.w = pk2(gb[2] - bflo(ah.w), gb[3] - bfhi(ah.w));
;                         const bf16x8 gah = __builtin_bit_cast(bf16x8, ah), gal = __builtin_bit_cast(bf16x8, al);
;                         f32x16 zacc;
; #pragma unroll
;                         for (int i = 0; i < 16; ++i) zacc[i] = zbias;
;                         zacc = MFMA32(gah, wbh, zacc); zacc = MFMA32(gal, wbh, zacc); zacc = MFMA32(gah, wbl, zacc);
; #pragma unroll
;                         for (int i = 0; i < 16; ++i) *(LAS float*)(lds + G2_Z + (((i & 3) + 8 * (i >> 2) + 4 * hh) * 128 + 32 * zd + r) * 4) = zacc[i];
.LBB0_220:
	s_waitcnt vmcnt(0)
	v_cvt_pk_bf16_f32 v102, v44, v45
	v_lshlrev_b32_e32 v16, 16, v102
	v_and_b32_e32 v17, 0xffff0000, v102
	v_cvt_pk_bf16_f32 v103, v46, v47
	v_cvt_pk_bf16_f32 v104, v40, v41
	v_cvt_pk_bf16_f32 v105, v42, v43
	v_pk_add_f32 v[16:17], v[44:45], v[16:17] neg_lo:[0,1] neg_hi:[0,1]
	s_and_b64 s[6:7], s[48:49], exec
	v_cvt_pk_bf16_f32 v44, v16, v17
	v_lshlrev_b32_e32 v16, 16, v103
	v_and_b32_e32 v17, 0xffff0000, v103
	v_pk_add_f32 v[16:17], v[46:47], v[16:17] neg_lo:[0,1] neg_hi:[0,1]
	s_cselect_b32 s0, s20, s8
	v_cvt_pk_bf16_f32 v45, v16, v17
	v_lshlrev_b32_e32 v16, 16, v104
	v_and_b32_e32 v17, 0xffff0000, v104
	v_pk_add_f32 v[16:17], v[40:41], v[16:17] neg_lo:[0,1] neg_hi:[0,1]
	v_lshlrev_b32_e32 v40, 16, v105
	v_cvt_pk_bf16_f32 v46, v16, v17
	v_mfma_f32_32x32x16_bf16 v[16:31], v[102:105], v[32:35], v[0:15]
	v_and_b32_e32 v41, 0xffff0000, v105
	v_add_f32_e64 v40, v42, -v40
	v_add_f32_e64 v41, v43, -v41
	s_lshl_b32 s0, s0, 5
	v_cvt_pk_bf16_f32 v47, v40, v41
	s_add_i32 s0, s0, s9
	s_mulk_i32 s0, 0x1a00
	s_or_b32 s6, s0, 0x1a00
	v_mfma_f32_32x32x16_bf16 v[16:31], v[44:47], v[32:35], v[16:31]
	s_or_b32 s7, s0, 0x3400
	s_add_i32 s15, s0, 0x4e00
	s_add_i32 s21, s0, 0x6800
	s_add_i32 s24, s0, 0x8200
	s_add_i32 s25, s0, 0x9c00
	s_add_i32 s26, s0, 0xb600
	s_add_i32 s28, s0, 0xd000
	s_add_i32 s33, s0, 0xea00
	s_add_i32 s78, s0, 0x10400
	s_add_i32 s79, s0, 0x11e00
	s_add_i32 s80, s0, 0x13800
	s_add_i32 s81, s0, 0x15200
	s_add_i32 s82, s0, 0x16c00
	s_add_i32 s83, s0, 0x18600
	s_cmp_lt_u32 s20, 63
	buffer_load_ushort v98, v50, s[64:67], s0 offen
	buffer_load_ushort v100, v50, s[64:67], s6 offen
	buffer_load_ushort v94, v50, s[64:67], s7 offen
	buffer_load_ushort v96, v50, s[64:67], s15 offen
	buffer_load_ushort v90, v50, s[64:67], s21 offen
	buffer_load_ushort v92, v50, s[64:67], s24 offen
	buffer_load_ushort v82, v50, s[64:67], s25 offen
	buffer_load_ushort v84, v50, s[64:67], s26 offen
	buffer_load_ushort v99, v53, s[64:67], s0 offen
	buffer_load_ushort v101, v53, s[64:67], s6 offen
	buffer_load_ushort v95, v53, s[64:67], s7 offen
	buffer_load_ushort v97, v53, s[64:67], s15 offen
	buffer_load_ushort v91, v53, s[64:67], s21 offen
	buffer_load_ushort v93, v53, s[64:67], s24 offen
	buffer_load_ushort v83, v53, s[64:67], s25 offen
	buffer_load_ushort v85, v53, s[64:67], s26 offen
	buffer_load_ushort v86, v50, s[64:67], s28 offen
	buffer_load_ushort v88, v50, s[64:67], s33 offen
	buffer_load_ushort v78, v50, s[64:67], s78 offen
	buffer_load_ushort v80, v50, s[64:67], s79 offen
	buffer_load_ushort v74, v50, s[64:67], s80 offen
	buffer_load_ushort v76, v50, s[64:67], s81 offen
	buffer_load_ushort v70, v50, s[64:67], s82 offen
	buffer_load_ushort v72, v50, s[64:67], s83 offen
	buffer_load_ushort v87, v53, s[64:67], s28 offen
	buffer_load_ushort v89, v53, s[64:67], s33 offen
	buffer_load_ushort v79, v53, s[64:67], s78 offen
	buffer_load_ushort v81, v53, s[64:67], s79 offen
	buffer_load_ushort v75, v53, s[64:67], s80 offen
	buffer_load_ushort v77, v53, s[64:67], s81 offen
	buffer_load_ushort v71, v53, s[64:67], s82 offen
	buffer_load_ushort v73, v53, s[64:67], s83 offen
	buffer_load_dword v68, v51, s[64:67], s0 offen
	buffer_load_dword v69, v51, s[64:67], s6 offen
	buffer_load_dword v66, v51, s[64:67], s7 offen
	buffer_load_dword v67, v51, s[64:67], s15 offen
	buffer_load_dword v64, v51, s[64:67], s21 offen
	buffer_load_dword v65, v51, s[64:67], s24 offen
	buffer_load_dword v62, v51, s[64:67], s25 offen
	buffer_load_dword v63, v51, s[64:67], s26 offen
	buffer_load_dword v60, v51, s[64:67], s28 offen
	buffer_load_dword v61, v51, s[64:67], s33 offen
	buffer_load_dword v58, v51, s[64:67], s78 offen
	buffer_load_dword v59, v51, s[64:67], s79 offen
	buffer_load_dword v56, v51, s[64:67], s80 offen
	buffer_load_dword v57, v51, s[64:67], s81 offen
	buffer_load_dword v54, v51, s[64:67], s82 offen
	buffer_load_dword v55, v51, s[64:67], s83 offen
	s_cselect_b64 s[6:7], -1, 0
	s_cmp_lg_u64 s[6:7], 0
	s_addc_u32 s0, s20, 0
	s_cmp_lg_u64 s[6:7], 0
	s_subb_u32 s6, 0, 0
	v_mfma_f32_32x32x16_bf16 v[16:31], v[102:105], v[36:39], v[16:31]
	s_add_i32 s15, s8, s6
	s_and_b64 s[6:7], s[48:49], exec
	s_cselect_b32 s0, s0, s15
	v_lshl_add_u32 v40, s0, 5, v52
	v_ashrrev_i32_e32 v41, 31, v40
	v_lshlrev_b64 v[40:41], 7, v[40:41]
	v_lshl_add_u64 v[44:45], v[48:49], 0, v[40:41]
	global_load_dwordx4 v[40:43], v[44:45], off offset:16
	s_nop 0
	global_load_dwordx4 v[44:47], v[44:45], off
	s_nop 1
	ds_write_b32 v214, v16
	ds_write_b32 v215, v17
	ds_write_b32 v216, v18
	ds_write_b32 v217, v19
	ds_write_b32 v218, v20
	ds_write_b32 v219, v21
	ds_write_b32 v220, v22
	ds_write_b32 v221, v23
	ds_write_b32 v222, v24
	ds_write_b32 v223, v25
	ds_write_b32 v224, v26
	ds_write_b32 v225, v27
	ds_write_b32 v226, v28
	ds_write_b32 v227, v29
	ds_write_b32 v228, v30
	ds_write_b32 v229, v31
	s_waitcnt lgkmcnt(0)
	s_barrier
; #define LAS __attribute__((address_space(3)))
; __device__ __forceinline__ void gla_scan_phase2(LAS unsigned char* lds, const bf16_t* proj, const float* gbuf, const float* wgu  , const float* bg  ,
;                                                 bf16_t* ob0, bf16_t* ob1) {
;     ...
;                     float cs[16];
; #pragma unroll
;                     for (int ii = 0; ii < 16; ++ii) {
;                         const float z = *(const LAS float*)(lds + G2_Z + ((16 * seg + ii) * 128 + d) * 4);
;                         cs[ii] = fminf(z, 0.f) * (1.4426950408889634f / 16.f) - __builtin_amdgcn_logf(1.f + __builtin_amdgcn_exp2f(fabsf(z) * -1.4426950408889634f)) * (1.f / 16.f);
;                     }
;                     if (dir == 0) {
; #pragma unroll
;                         for (int ii = 1; ii < 16; ++ii) cs[ii] += cs[ii - 1];
;                         *(LAS float*)(lds + G2_SEG + (seg * 128 + d) * 4) = cs[15];
;                     } else {
; #pragma unroll
;     ...
;                         *(LAS float*)(lds + G2_SEG + (seg * 128 + d) * 4) = cs[0];
;                     }
	ds_read2st64_b32 v[118:119], v230 offset1:2
	ds_read2st64_b32 v[120:121], v230 offset0:4 offset1:6
	ds_read2st64_b32 v[122:123], v230 offset0:8 offset1:10
	ds_read2st64_b32 v[124:125], v230 offset0:12 offset1:14
	ds_read2st64_b32 v[126:127], v230 offset0:16 offset1:18
	ds_read2st64_b32 v[128:129], v230 offset0:20 offset1:22
	ds_read2st64_b32 v[130:131], v230 offset0:24 offset1:26
	ds_read2st64_b32 v[132:133], v230 offset0:28 offset1:30
	s_andn2_b64 vcc, exec, s[68:69]
	s_mov_b64 s[6:7], -1
	s_waitcnt lgkmcnt(4)
	v_mul_f32_e64 v134, |v118|, s1
	v_mul_f32_e64 v135, |v119|, s1
	v_mul_f32_e64 v136, |v120|, s1
	v_mul_f32_e64 v137, |v121|, s1
	v_mul_f32_e64 v138, |v122|, s1
	v_mul_f32_e64 v139, |v123|, s1
	v_mul_f32_e64 v140, |v124|, s1
	v_mul_f32_e64 v141, |v125|, s1
	s_waitcnt lgkmcnt(0)
	v_mul_f32_e64 v142, |v126|, s1
	v_mul_f32_e64 v143, |v127|, s1
	v_mul_f32_e64 v144, |v128|, s1
	v_mul_f32_e64 v145, |v129|, s1
	v_mul_f32_e64 v146, |v130|, s1
	v_mul_f32_e64 v147, |v131|, s1
	v_mul_f32_e64 v148, |v132|, s1
	v_mul_f32_e64 v149, |v133|, s1
	v_exp_f32_e32 v134, v134
	v_exp_f32_e32 v135, v135
	v_exp_f32_e32 v136, v136
	v_exp_f32_e32 v137, v137
	v_exp_f32_e32 v138, v138
	v_exp_f32_e32 v139, v139
	v_exp_f32_e32 v140, v140
	v_exp_f32_e32 v141, v141
	v_exp_f32_e32 v142, v142
	v_exp_f32_e32 v143, v143
	v_exp_f32_e32 v144, v144
	v_exp_f32_e32 v145, v145
	v_exp_f32_e32 v146, v146
	v_exp_f32_e32 v147, v147
	v_exp_f32_e32 v148, v148
	v_exp_f32_e32 v149, v149
	v_min_f32_e32 v118, 0, v118
	v_min_f32_e32 v119, 0, v119
	v_min_f32_e32 v120, 0, v120
	v_min_f32_e32 v121, 0, v121
	v_min_f32_e32 v122, 0, v122
	v_min_f32_e32 v123, 0, v123
	v_min_f32_e32 v124, 0, v124
	v_min_f32_e32 v125, 0, v125
	v_min_f32_e32 v126, 0, v126
	v_min_f32_e32 v127, 0, v127
	v_min_f32_e32 v128, 0, v128
	v_min_f32_e32 v129, 0, v129
	v_min_f32_e32 v130, 0, v130
	v_min_f32_e32 v131, 0, v131
	v_min_f32_e32 v132, 0, v132
	v_min_f32_e32 v133, 0, v133
	v_add_f32_e32 v134, 1.0, v134
	v_add_f32_e32 v135, 1.0, v135
	v_add_f32_e32 v136, 1.0, v136
	v_add_f32_e32 v137, 1.0, v137
	v_add_f32_e32 v138, 1.0, v138
	v_add_f32_e32 v139, 1.0, v139
	v_add_f32_e32 v140, 1.0, v140
	v_add_f32_e32 v141, 1.0, v141
	v_add_f32_e32 v142, 1.0, v142
	v_add_f32_e32 v143, 1.0, v143
	v_add_f32_e32 v144, 1.0, v144
	v_add_f32_e32 v145, 1.0, v145
	v_add_f32_e32 v146, 1.0, v146
	v_add_f32_e32 v147, 1.0, v147
	v_add_f32_e32 v148, 1.0, v148
	v_add_f32_e32 v149, 1.0, v149
	v_log_f32_e32 v134, v134
	v_log_f32_e32 v135, v135
	v_log_f32_e32 v136, v136
	v_log_f32_e32 v137, v137
	v_log_f32_e32 v138, v138
	v_log_f32_e32 v139, v139
	v_log_f32_e32 v140, v140
	v_log_f32_e32 v141, v141
	v_log_f32_e32 v142, v142
	v_log_f32_e32 v143, v143
	v_log_f32_e32 v144, v144
	v_log_f32_e32 v145, v145
	v_log_f32_e32 v146, v146
	v_log_f32_e32 v147, v147
	v_log_f32_e32 v148, v148
	v_log_f32_e32 v149, v149
	v_mul_f32_e32 v134, 0x3d800000, v134
	v_mul_f32_e32 v135, 0x3d800000, v135
	v_mul_f32_e32 v136, 0x3d800000, v136
	v_mul_f32_e32 v137, 0x3d800000, v137
	v_mul_f32_e32 v138, 0x3d800000, v138
	v_mul_f32_e32 v139, 0x3d800000, v139
	v_mul_f32_e32 v140, 0x3d800000, v140
	v_mul_f32_e32 v141, 0x3d800000, v141
	v_mul_f32_e32 v142, 0x3d800000, v142
	v_mul_f32_e32 v143, 0x3d800000, v143
	v_mul_f32_e32 v144, 0x3d800000, v144
	v_mul_f32_e32 v145, 0x3d800000, v145
	v_mul_f32_e32 v146, 0x3d800000, v146
	v_mul_f32_e32 v147, 0x3d800000, v147
	v_mul_f32_e32 v148, 0x3d800000, v148
	v_mul_f32_e32 v149, 0x3d800000, v149
	v_fma_f32 v16, v118, s10, -v134
	v_fma_f32 v25, v119, s10, -v135
	v_fma_f32 v26, v120, s10, -v136
	v_fma_f32 v29, v121, s10, -v137
	v_fma_f32 v30, v122, s10, -v138
	v_fma_f32 v102, v123, s10, -v139
	v_fma_f32 v104, v124, s10, -v140
	v_fma_f32 v105, v125, s10, -v141
	v_fma_f32 v108, v126, s10, -v142
	v_fma_f32 v109, v127, s10, -v143
	v_fma_f32 v111, v128, s10, -v144
	v_fma_f32 v112, v129, s10, -v145
	v_fma_f32 v113, v130, s10, -v146
	v_fma_f32 v114, v131, s10, -v147
	v_fma_f32 v116, v132, s10, -v148
	v_fma_f32 v17, v133, s10, -v149
	s_cbranch_vccnz .LBB0_222
	v_add_f32_e32 v18, v116, v17
	v_add_f32_e32 v19, v114, v18
	v_add_f32_e32 v20, v113, v19
	v_add_f32_e32 v21, v112, v20
	v_add_f32_e32 v22, v111, v21
	v_add_f32_e32 v23, v109, v22
	v_add_f32_e32 v24, v108, v23
	v_add_f32_e32 v27, v105, v24
	v_add_f32_e32 v28, v104, v27
	v_add_f32_e32 v31, v102, v28
	v_add_f32_e32 v103, v30, v31
	v_add_f32_e32 v106, v29, v103
	v_add_f32_e32 v107, v26, v106
	v_add_f32_e32 v110, v25, v107
	v_add_f32_e32 v115, v16, v110
	s_mov_b64 s[6:7], 0

; #define LAS __attribute__((address_space(3)))
; __device__ __forceinline__ unsigned pk2(float lo, float hi) { f32x2 v = {lo, hi}; bf16x2_t b = __builtin_convertvector(v, bf16x2_t); return __builtin_bit_cast(unsigned, b); }
; __device__ __forceinline__ float bflo(unsigned w) { return __uint_as_float(w << 16); }
; __device__ __forceinline__ float bfhi(unsigned w) { return __uint_as_float(w & 0xffff0000u); }
;     __device__ __forceinline__ void operator()(const f32x4 (&acc)[2][2][4][2], const Unit& u, int wr, int wc, int fr, int fq, LAS unsigned char* lds, int tid, State& st) const {
;         const int col0 = u.pn * BM + wc * 32 + 8 * fq;
;         LAS float* RED = (LAS float*)(lds + STAGE_BYTES);
; #pragma unroll
;         for (int ai = 0; ai < 2; ++ai) {
;             u32x4 bw[4][2];
; #pragma unroll
;             for (int m = 0; m < 4; ++m)
; #pragma unroll
;                 for (int bj = 0; bj < 2; ++bj) bw[m][bj] = *(const u32x4*)(xin + (size_t)(u.pm * BM + ai * HALF + wr * 64 + m * 16 + fr) * DM + col0 + bj * HALF);
; #pragma unroll
;             for (int m = 0; m < 4; ++m) {
;                 const int rl = ai * HALF + wr * 64 + m * 16 + fr;
;                 bf16_t* xp = xb + (size_t)(u.pm * BM + rl) * DM + col0;
;                 float sq = 0.f;
; #pragma unroll
;                 for (int bj = 0; bj < 2; ++bj) {
;                     const u32x4 w0 = bw[m][bj];
;                     const f32x4 o0 = (f32x4){bflo(w0.x), bfhi(w0.x), bflo(w0.y), bfhi(w0.y)} + acc[ai][bj][m][0];
;                     const f32x4 o1 = (f32x4){bflo(w0.z), bfhi(w0.z), bflo(w0.w), bfhi(w0.w)} + acc[ai][bj][m][1];
;                     sq += ((o0[0] * o0[0] + o0[1] * o0[1]) + (o0[2] * o0[2] + o0[3] * o0[3])) + ((o1[0] * o1[0] + o1[1] * o1[1]) + (o1[2] * o1[2] + o1[3] * o1[3]));
;                     u32x4 w; w.x = pk2(o0[0], o0[1]); w.y = pk2(o0[2], o0[3]); w.z = pk2(o1[0], o1[1]); w.w = pk2(o1[2], o1[3]);
;                     *(u32x4*)(xp + bj * HALF) = w;
;                 }
;                 sq += __shfl_xor(sq, 16); sq += __shfl_xor(sq, 32);
;                 if (fq == 0) RED[wc * 256 + rl] = sq;
.LBB0_631:
	v_and_b32_e32 v129, 64, v194
	v_xor_b32_e32 v128, 16, v194
	v_add_u32_e32 v129, 64, v129
	v_cmp_lt_i32_e32 vcc, v128, v129
	v_lshl_or_b32 v164, s12, 8, v175
	s_lshl_b32 s9, s48, 8
	v_cndmask_b32_e32 v128, v194, v128, vcc
	v_add_u32_e32 v166, s9, v173
	v_ashrrev_i32_e32 v165, 31, v164
	v_lshlrev_b32_e32 v193, 2, v128
	v_xor_b32_e32 v128, 32, v194
	v_cmp_lt_i32_e32 vcc, v128, v129
	v_lshlrev_b64 v[170:171], 1, v[164:165]
	v_ashrrev_i32_e32 v167, 31, v166
	v_cndmask_b32_e32 v128, v194, v128, vcc
	v_lshl_add_u64 v[168:169], s[84:85], 0, v[170:171]
	v_lshlrev_b64 v[200:201], 11, v[166:167]
	v_lshlrev_b32_e32 v192, 2, v128
	v_lshl_add_u64 v[128:129], v[168:169], 0, v[200:201]
	global_load_dwordx4 v[196:199], v[128:129], off
	global_load_dwordx4 v[152:155], v[128:129], off offset:256
	v_or_b32_e32 v128, 16, v166
	v_ashrrev_i32_e32 v129, 31, v128
	v_lshlrev_b64 v[128:129], 11, v[128:129]
	v_lshl_add_u64 v[128:129], v[168:169], 0, v[128:129]
	global_load_dwordx4 v[148:151], v[128:129], off
	global_load_dwordx4 v[144:147], v[128:129], off offset:256
	v_or_b32_e32 v128, 32, v166
	v_ashrrev_i32_e32 v129, 31, v128
	v_lshlrev_b64 v[128:129], 11, v[128:129]
	v_lshl_add_u64 v[128:129], v[168:169], 0, v[128:129]
	global_load_dwordx4 v[140:143], v[128:129], off
	global_load_dwordx4 v[136:139], v[128:129], off offset:256
	v_or_b32_e32 v128, 48, v166
	v_ashrrev_i32_e32 v129, 31, v128
	v_lshlrev_b64 v[128:129], 11, v[128:129]
	v_lshl_add_u64 v[128:129], v[168:169], 0, v[128:129]
	global_load_dwordx4 v[132:135], v[128:129], off
	s_nop 0
	global_load_dwordx4 v[128:131], v[128:129], off offset:256
	v_lshl_add_u64 v[200:201], s[84:85], 0, v[200:201]
	v_lshl_add_u64 v[170:171], v[200:201], 0, v[170:171]
	v_add_u32_e32 v230, 0x80, v166
	v_ashrrev_i32_e32 v231, 31, v230
	v_lshlrev_b64 v[230:231], 11, v[230:231]
	v_lshl_add_u64 v[230:231], v[168:169], 0, v[230:231]
	global_load_dwordx4 v[202:205], v[230:231], off
	global_load_dwordx4 v[206:209], v[230:231], off offset:256
	v_add_u32_e32 v230, 0x90, v166
	v_ashrrev_i32_e32 v231, 31, v230
	v_lshlrev_b64 v[230:231], 11, v[230:231]
	v_lshl_add_u64 v[230:231], v[168:169], 0, v[230:231]
	global_load_dwordx4 v[210:213], v[230:231], off
	global_load_dwordx4 v[214:217], v[230:231], off offset:256
	v_add_u32_e32 v230, 0xa0, v166
	v_ashrrev_i32_e32 v231, 31, v230
	v_lshlrev_b64 v[230:231], 11, v[230:231]
	v_lshl_add_u64 v[230:231], v[168:169], 0, v[230:231]
	global_load_dwordx4 v[218:221], v[230:231], off
	global_load_dwordx4 v[222:225], v[230:231], off offset:256
	v_add_u32_e32 v230, 0xb0, v166
	v_ashrrev_i32_e32 v231, 31, v230
	v_lshlrev_b64 v[230:231], 11, v[230:231]
	v_lshl_add_u64 v[230:231], v[168:169], 0, v[230:231]
	global_load_dwordx4 v[226:229], v[230:231], off
	s_waitcnt vmcnt(7)
	v_lshlrev_b32_e32 v200, 16, v196
	v_and_b32_e32 v201, 0xffff0000, v196
	v_lshlrev_b32_e32 v196, 16, v197
	v_and_b32_e32 v197, 0xffff0000, v197
	v_pk_add_f32 v[126:127], v[126:127], v[196:197]
	v_pk_add_f32 v[124:125], v[124:125], v[200:201]
	v_lshlrev_b32_e32 v196, 16, v198
	v_and_b32_e32 v197, 0xffff0000, v198
	v_lshlrev_b32_e32 v198, 16, v199
	v_and_b32_e32 v199, 0xffff0000, v199
	v_pk_add_f32 v[198:199], v[122:123], v[198:199]
	v_pk_add_f32 v[122:123], v[120:121], v[196:197]
	v_mul_f32_e32 v120, v125, v125
	v_mul_f32_e32 v121, v127, v127
	v_fmac_f32_e32 v120, v124, v124
	v_fmac_f32_e32 v121, v126, v126
	v_add_f32_e32 v120, v120, v121
	v_mul_f32_e32 v121, v123, v123
	v_mul_f32_e32 v167, v199, v199
	v_fmac_f32_e32 v121, v122, v122
	v_fmac_f32_e32 v167, v198, v198
	v_add_f32_e32 v121, v121, v167
	v_add_f32_e32 v167, v120, v121
	v_cvt_pk_bf16_f32 v120, v124, v125
	v_cvt_pk_bf16_f32 v121, v126, v127
	v_cvt_pk_bf16_f32 v122, v122, v123
	v_cvt_pk_bf16_f32 v123, v198, v199
	global_load_dwordx4 v[196:199], v[230:231], off offset:256
	global_store_dwordx4 v[170:171], v[120:123], off
	s_nop 1
	v_lshlrev_b32_e32 v120, 16, v152
	v_and_b32_e32 v121, 0xffff0000, v152
	v_lshlrev_b32_e32 v122, 16, v153
	v_and_b32_e32 v123, 0xffff0000, v153
	v_pk_add_f32 v[118:119], v[118:119], v[122:123]
	v_pk_add_f32 v[116:117], v[116:117], v[120:121]
	v_lshlrev_b32_e32 v120, 16, v154
	v_and_b32_e32 v121, 0xffff0000, v154
	v_lshlrev_b32_e32 v122, 16, v155
	v_and_b32_e32 v123, 0xffff0000, v155
	v_pk_add_f32 v[122:123], v[114:115], v[122:123]
	v_pk_add_f32 v[114:115], v[112:113], v[120:121]
	v_mul_f32_e32 v112, v117, v117
	v_mul_f32_e32 v113, v119, v119
	v_fmac_f32_e32 v112, v116, v116
	v_fmac_f32_e32 v113, v118, v118
	v_add_f32_e32 v112, v112, v113
	v_mul_f32_e32 v113, v115, v115
	v_mul_f32_e32 v120, v123, v123
	v_fmac_f32_e32 v113, v114, v114
	v_fmac_f32_e32 v120, v122, v122
	v_add_f32_e32 v113, v113, v120
	v_add_f32_e32 v112, v112, v113
	v_add_f32_e32 v120, v167, v112
	v_cvt_pk_bf16_f32 v112, v116, v117
	v_cvt_pk_bf16_f32 v113, v118, v119
	v_cvt_pk_bf16_f32 v114, v114, v115
	v_cvt_pk_bf16_f32 v115, v122, v123
	global_store_dwordx4 v[170:171], v[112:115], off offset:256
	ds_bpermute_b32 v112, v193, v120
	s_waitcnt lgkmcnt(0)
	v_add_f32_e32 v112, v120, v112
	ds_bpermute_b32 v113, v192, v112
	s_and_saveexec_b64 s[6:7], s[38:39]
	s_cbranch_execz .LBB0_633
	s_waitcnt lgkmcnt(0)
	v_add_f32_e32 v112, v112, v113
	ds_write_b32 v176, v112

; __device__ __forceinline__ unsigned pk2(float lo, float hi) { f32x2 v = {lo, hi}; bf16x2_t b = __builtin_convertvector(v, bf16x2_t); return __builtin_bit_cast(unsigned, b); }
; __device__ __forceinline__ float bflo(unsigned w) { return __uint_as_float(w << 16); }
; __device__ __forceinline__ float bfhi(unsigned w) { return __uint_as_float(w & 0xffff0000u); }
;     __device__ __forceinline__ void operator()(const f32x4 (&acc)[2][2][4][2], const Unit& u, int wr, int wc, int fr, int fq, LAS unsigned char* lds, int tid, State& st) const {
;     ...
;                 for (int bj = 0; bj < 2; ++bj) bw[m][bj] = *(const u32x4*)(xin + (size_t)(u.pm * BM + ai * HALF + wr * 64 + m * 16 + fr) * DM + col0 + bj * HALF);
; #pragma unroll
;             for (int m = 0; m < 4; ++m) {
;                 const int rl = ai * HALF + wr * 64 + m * 16 + fr;
;                 bf16_t* xp = xb + (size_t)(u.pm * BM + rl) * DM + col0;
;                 float sq = 0.f;
; #pragma unroll
;                 for (int bj = 0; bj < 2; ++bj) {
;                     const u32x4 w0 = bw[m][bj];
;                     const f32x4 o0 = (f32x4){bflo(w0.x), bfhi(w0.x), bflo(w0.y), bfhi(w0.y)} + acc[ai][bj][m][0];
;                     const f32x4 o1 = (f32x4){bflo(w0.z), bfhi(w0.z), bflo(w0.w), bfhi(w0.w)} + acc[ai][bj][m][1];
;                     sq += ((o0[0] * o0[0] + o0[1] * o0[1]) + (o0[2] * o0[2] + o0[3] * o0[3])) + ((o1[0] * o1[0] + o1[1] * o1[1]) + (o1[2] * o1[2] + o1[3] * o1[3]));
;                     u32x4 w; w.x = pk2(o0[0], o0[1]); w.y = pk2(o0[2], o0[3]); w.z = pk2(o1[0], o1[1]); w.w = pk2(o1[2], o1[3]);
;                     *(u32x4*)(xp + bj * HALF) = w;
;                 }
;                 sq += __shfl_xor(sq, 16); sq += __shfl_xor(sq, 32);
;                 if (fq == 0) RED[wc * 256 + rl] = sq;
.LBB0_639:
	s_or_b64 exec, exec, s[6:7]
	v_add_u32_e32 v64, 0x80, v166
	s_waitcnt lgkmcnt(0)
	v_ashrrev_i32_e32 v65, 31, v64
	v_lshlrev_b64 v[98:99], 11, v[64:65]
	v_lshl_add_u64 v[64:65], v[168:169], 0, v[98:99]
	s_waitcnt vmcnt(8)
	v_mov_b32_e32 v100, v202
	v_mov_b32_e32 v101, v203
	v_mov_b32_e32 v102, v204
	v_mov_b32_e32 v103, v205
	v_mov_b32_e32 v88, v206
	v_mov_b32_e32 v89, v207
	v_mov_b32_e32 v90, v208
	v_mov_b32_e32 v91, v209
	v_add_u32_e32 v64, 0x90, v166
	v_ashrrev_i32_e32 v65, 31, v64
	v_lshlrev_b64 v[96:97], 11, v[64:65]
	v_lshl_add_u64 v[64:65], v[168:169], 0, v[96:97]
	v_mov_b32_e32 v84, v210
	v_mov_b32_e32 v85, v211
	v_mov_b32_e32 v86, v212
	v_mov_b32_e32 v87, v213
	v_mov_b32_e32 v80, v214
	v_mov_b32_e32 v81, v215
	v_mov_b32_e32 v82, v216
	v_mov_b32_e32 v83, v217
	v_add_u32_e32 v64, 0xa0, v166
	v_ashrrev_i32_e32 v65, 31, v64
	v_lshlrev_b64 v[94:95], 11, v[64:65]
	v_lshl_add_u64 v[64:65], v[168:169], 0, v[94:95]
	v_mov_b32_e32 v76, v218
	v_mov_b32_e32 v77, v219
	v_mov_b32_e32 v78, v220
	v_mov_b32_e32 v79, v221
	v_mov_b32_e32 v72, v222
	v_mov_b32_e32 v73, v223
	v_mov_b32_e32 v74, v224
	v_mov_b32_e32 v75, v225
	v_add_u32_e32 v64, 0xb0, v166
	v_ashrrev_i32_e32 v65, 31, v64
	v_lshlrev_b64 v[92:93], 11, v[64:65]
	v_lshl_add_u64 v[64:65], v[168:169], 0, v[92:93]
	v_mov_b32_e32 v68, v226
	v_mov_b32_e32 v69, v227
	v_mov_b32_e32 v70, v228
	v_mov_b32_e32 v71, v229
	s_nop 0
	v_mov_b32_e32 v64, v196
	v_mov_b32_e32 v65, v197
	v_mov_b32_e32 v66, v198
	v_mov_b32_e32 v67, v199
	v_lshl_add_u64 v[98:99], s[84:85], 0, v[98:99]
	v_lshl_add_u64 v[98:99], v[164:165], 1, v[98:99]
	s_nop 0
	v_lshlrev_b32_e32 v104, 16, v100
	v_and_b32_e32 v105, 0xffff0000, v100
	v_lshlrev_b32_e32 v100, 16, v101
	v_and_b32_e32 v101, 0xffff0000, v101
	v_pk_add_f32 v[62:63], v[62:63], v[100:101]
	v_pk_add_f32 v[60:61], v[60:61], v[104:105]
	v_lshlrev_b32_e32 v100, 16, v102
	v_and_b32_e32 v101, 0xffff0000, v102
	v_lshlrev_b32_e32 v102, 16, v103
	v_and_b32_e32 v103, 0xffff0000, v103
	v_pk_add_f32 v[102:103], v[58:59], v[102:103]
	v_pk_add_f32 v[58:59], v[56:57], v[100:101]
	v_mul_f32_e32 v56, v61, v61
	v_mul_f32_e32 v57, v63, v63
	v_fmac_f32_e32 v56, v60, v60
	v_fmac_f32_e32 v57, v62, v62
	v_add_f32_e32 v56, v56, v57
	v_mul_f32_e32 v57, v59, v59
	v_mul_f32_e32 v100, v103, v103
	v_fmac_f32_e32 v57, v58, v58
	v_fmac_f32_e32 v100, v102, v102
	v_add_f32_e32 v57, v57, v100
	v_add_f32_e32 v100, v56, v57
	v_cvt_pk_bf16_f32 v56, v60, v61
	v_cvt_pk_bf16_f32 v57, v62, v63
	v_cvt_pk_bf16_f32 v58, v58, v59
	v_cvt_pk_bf16_f32 v59, v102, v103
	global_store_dwordx4 v[98:99], v[56:59], off
	s_nop 0
	s_nop 0
	v_lshlrev_b32_e32 v56, 16, v88
	v_and_b32_e32 v57, 0xffff0000, v88
	v_lshlrev_b32_e32 v58, 16, v89
	v_and_b32_e32 v59, 0xffff0000, v89
	v_pk_add_f32 v[54:55], v[54:55], v[58:59]
	v_pk_add_f32 v[52:53], v[52:53], v[56:57]
	v_lshlrev_b32_e32 v56, 16, v90
	v_and_b32_e32 v57, 0xffff0000, v90
	v_lshlrev_b32_e32 v58, 16, v91
	v_and_b32_e32 v59, 0xffff0000, v91
	v_pk_add_f32 v[58:59], v[50:51], v[58:59]
	v_pk_add_f32 v[50:51], v[48:49], v[56:57]
	v_mul_f32_e32 v48, v53, v53
	v_mul_f32_e32 v49, v55, v55
	v_fmac_f32_e32 v48, v52, v52
	v_fmac_f32_e32 v49, v54, v54
	v_add_f32_e32 v48, v48, v49
	v_mul_f32_e32 v49, v51, v51
	v_mul_f32_e32 v56, v59, v59
	v_fmac_f32_e32 v49, v50, v50
	v_fmac_f32_e32 v56, v58, v58
	v_add_f32_e32 v49, v49, v56
	v_add_f32_e32 v48, v48, v49
	v_add_f32_e32 v56, v100, v48
	v_cvt_pk_bf16_f32 v48, v52, v53
	v_cvt_pk_bf16_f32 v49, v54, v55
	v_cvt_pk_bf16_f32 v50, v50, v51
	v_cvt_pk_bf16_f32 v51, v58, v59
	global_store_dwordx4 v[98:99], v[48:51], off offset:256
	ds_bpermute_b32 v48, v193, v56
	s_waitcnt lgkmcnt(0)
	v_add_f32_e32 v48, v56, v48
	ds_bpermute_b32 v49, v192, v48
	s_and_saveexec_b64 s[6:7], s[38:39]
	s_cbranch_execz .LBB0_641
	s_waitcnt lgkmcnt(0)
	v_add_f32_e32 v48, v48, v49
	ds_write_b32 v176, v48 offset:512
.LBB0_641:
	s_or_b64 exec, exec, s[6:7]
	s_nop 0
	v_lshlrev_b32_e32 v50, 16, v84
	v_and_b32_e32 v51, 0xffff0000, v84
	v_lshlrev_b32_e32 v52, 16, v85
	v_and_b32_e32 v53, 0xffff0000, v85
	v_pk_add_f32 v[46:47], v[46:47], v[52:53]
	v_pk_add_f32 v[44:45], v[44:45], v[50:51]
	v_lshlrev_b32_e32 v50, 16, v86
	v_and_b32_e32 v51, 0xffff0000, v86
	v_lshlrev_b32_e32 v52, 16, v87
	v_and_b32_e32 v53, 0xffff0000, v87
	v_pk_add_f32 v[52:53], v[42:43], v[52:53]
	v_pk_add_f32 v[42:43], v[40:41], v[50:51]
	v_mul_f32_e32 v40, v45, v45
	v_mul_f32_e32 v41, v47, v47
	v_fmac_f32_e32 v40, v44, v44
	v_fmac_f32_e32 v41, v46, v46
	v_add_f32_e32 v40, v40, v41
	v_mul_f32_e32 v41, v43, v43
	v_mul_f32_e32 v50, v53, v53
	v_fmac_f32_e32 v41, v42, v42
	v_fmac_f32_e32 v50, v52, v52
	v_add_f32_e32 v41, v41, v50
	v_add_f32_e32 v50, v40, v41
	v_cvt_pk_bf16_f32 v40, v44, v45
	v_cvt_pk_bf16_f32 v41, v46, v47
	s_nop 0
	v_lshlrev_b32_e32 v44, 16, v80
	v_and_b32_e32 v45, 0xffff0000, v80
	v_lshlrev_b32_e32 v46, 16, v81
	v_and_b32_e32 v47, 0xffff0000, v81
	v_pk_add_f32 v[38:39], v[38:39], v[46:47]
	v_pk_add_f32 v[36:37], v[36:37], v[44:45]
	v_lshlrev_b32_e32 v44, 16, v82
	v_and_b32_e32 v45, 0xffff0000, v82
	v_lshlrev_b32_e32 v46, 16, v83
	v_and_b32_e32 v47, 0xffff0000, v83
	v_pk_add_f32 v[44:45], v[32:33], v[44:45]
	v_mul_f32_e32 v32, v37, v37
	v_mul_f32_e32 v33, v39, v39
	v_pk_add_f32 v[46:47], v[34:35], v[46:47]
	v_fmac_f32_e32 v32, v36, v36
	v_fmac_f32_e32 v33, v38, v38
	v_add_f32_e32 v32, v32, v33
	v_mul_f32_e32 v33, v45, v45
	v_mul_f32_e32 v34, v47, v47
	v_fmac_f32_e32 v33, v44, v44
	v_fmac_f32_e32 v34, v46, v46
	v_add_f32_e32 v33, v33, v34
	v_add_f32_e32 v32, v32, v33
	v_add_f32_e32 v32, v50, v32
	ds_bpermute_b32 v33, v193, v32
	s_waitcnt lgkmcnt(1)
	v_lshl_add_u64 v[48:49], s[84:85], 0, v[96:97]
	v_lshl_add_u64 v[48:49], v[164:165], 1, v[48:49]
	v_cvt_pk_bf16_f32 v42, v42, v43
	v_cvt_pk_bf16_f32 v43, v52, v53
	s_waitcnt lgkmcnt(0)
	v_add_f32_e32 v32, v32, v33
	ds_bpermute_b32 v33, v192, v32
	v_cvt_pk_bf16_f32 v34, v36, v37
	v_cvt_pk_bf16_f32 v35, v38, v39
	v_cvt_pk_bf16_f32 v36, v44, v45
	v_cvt_pk_bf16_f32 v37, v46, v47
	global_store_dwordx4 v[48:49], v[40:43], off
	global_store_dwordx4 v[48:49], v[34:37], off offset:256
	s_and_saveexec_b64 s[6:7], s[38:39]
	s_cbranch_execz .LBB0_643
	s_waitcnt lgkmcnt(0)
	v_add_f32_e32 v32, v32, v33
	ds_write_b32 v176, v32 offset:576
; __device__ __forceinline__ unsigned pk2(float lo, float hi) { f32x2 v = {lo, hi}; bf16x2_t b = __builtin_convertvector(v, bf16x2_t); return __builtin_bit_cast(unsigned, b); }
; __device__ __forceinline__ float bflo(unsigned w) { return __uint_as_float(w << 16); }
; __device__ __forceinline__ float bfhi(unsigned w) { return __uint_as_float(w & 0xffff0000u); }
;     __device__ __forceinline__ void operator()(const f32x4 (&acc)[2][2][4][2], const Unit& u, int wr, int wc, int fr, int fq, LAS unsigned char* lds, int tid, State& st) const {
;     ...
;                 for (int bj = 0; bj < 2; ++bj) bw[m][bj] = *(const u32x4*)(xin + (size_t)(u.pm * BM + ai * HALF + wr * 64 + m * 16 + fr) * DM + col0 + bj * HALF);
; #pragma unroll
;             for (int m = 0; m < 4; ++m) {
;                 const int rl = ai * HALF + wr * 64 + m * 16 + fr;
;                 bf16_t* xp = xb + (size_t)(u.pm * BM + rl) * DM + col0;
;                 float sq = 0.f;
; #pragma unroll
;                 for (int bj = 0; bj < 2; ++bj) {
;                     const u32x4 w0 = bw[m][bj];
;                     const f32x4 o0 = (f32x4){bflo(w0.x), bfhi(w0.x), bflo(w0.y), bfhi(w0.y)} + acc[ai][bj][m][0];
;                     const f32x4 o1 = (f32x4){bflo(w0.z), bfhi(w0.z), bflo(w0.w), bfhi(w0.w)} + acc[ai][bj][m][1];
;                     sq += ((o0[0] * o0[0] + o0[1] * o0[1]) + (o0[2] * o0[2] + o0[3] * o0[3])) + ((o1[0] * o1[0] + o1[1] * o1[1]) + (o1[2] * o1[2] + o1[3] * o1[3]));
;                     u32x4 w; w.x = pk2(o0[0], o0[1]); w.y = pk2(o0[2], o0[3]); w.z = pk2(o1[0], o1[1]); w.w = pk2(o1[2], o1[3]);
;                     *(u32x4*)(xp + bj * HALF) = w;
;                 }
;                 sq += __shfl_xor(sq, 16); sq += __shfl_xor(sq, 32);
;                 if (fq == 0) RED[wc * 256 + rl] = sq;
.LBB0_643:
	s_or_b64 exec, exec, s[6:7]
	s_nop 0
	v_lshlrev_b32_e32 v34, 16, v76
	v_and_b32_e32 v35, 0xffff0000, v76
	v_lshlrev_b32_e32 v36, 16, v77
	v_and_b32_e32 v37, 0xffff0000, v77
	v_pk_add_f32 v[30:31], v[30:31], v[36:37]
	v_pk_add_f32 v[28:29], v[28:29], v[34:35]
	v_lshlrev_b32_e32 v34, 16, v78
	v_and_b32_e32 v35, 0xffff0000, v78
	v_lshlrev_b32_e32 v36, 16, v79
	v_and_b32_e32 v37, 0xffff0000, v79
	v_pk_add_f32 v[36:37], v[26:27], v[36:37]
	v_pk_add_f32 v[26:27], v[24:25], v[34:35]
	v_mul_f32_e32 v24, v29, v29
	v_mul_f32_e32 v25, v31, v31
	v_fmac_f32_e32 v24, v28, v28
	v_fmac_f32_e32 v25, v30, v30
	v_add_f32_e32 v24, v24, v25
	v_mul_f32_e32 v25, v27, v27
	v_mul_f32_e32 v34, v37, v37
	v_fmac_f32_e32 v25, v26, v26
	v_fmac_f32_e32 v34, v36, v36
	v_add_f32_e32 v25, v25, v34
	v_add_f32_e32 v34, v24, v25
	v_cvt_pk_bf16_f32 v24, v28, v29
	v_cvt_pk_bf16_f32 v25, v30, v31
	s_nop 0
	v_lshlrev_b32_e32 v28, 16, v72
	v_and_b32_e32 v29, 0xffff0000, v72
	v_lshlrev_b32_e32 v30, 16, v73
	v_and_b32_e32 v31, 0xffff0000, v73
	v_pk_add_f32 v[22:23], v[22:23], v[30:31]
	v_pk_add_f32 v[20:21], v[20:21], v[28:29]
	v_lshlrev_b32_e32 v28, 16, v74
	v_and_b32_e32 v29, 0xffff0000, v74
	v_lshlrev_b32_e32 v30, 16, v75
	v_and_b32_e32 v31, 0xffff0000, v75
	v_pk_add_f32 v[28:29], v[16:17], v[28:29]
	v_mul_f32_e32 v16, v21, v21
	v_mul_f32_e32 v17, v23, v23
	v_pk_add_f32 v[30:31], v[18:19], v[30:31]
	v_fmac_f32_e32 v16, v20, v20
	v_fmac_f32_e32 v17, v22, v22
	v_add_f32_e32 v16, v16, v17
	v_mul_f32_e32 v17, v29, v29
	v_mul_f32_e32 v18, v31, v31
	v_fmac_f32_e32 v17, v28, v28
	v_fmac_f32_e32 v18, v30, v30
	v_add_f32_e32 v17, v17, v18
	v_add_f32_e32 v16, v16, v17
	v_add_f32_e32 v16, v34, v16
	ds_bpermute_b32 v17, v193, v16
	s_waitcnt lgkmcnt(1)
	v_lshl_add_u64 v[32:33], s[84:85], 0, v[94:95]
	v_lshl_add_u64 v[32:33], v[164:165], 1, v[32:33]
	v_cvt_pk_bf16_f32 v26, v26, v27
	v_cvt_pk_bf16_f32 v27, v36, v37
	s_waitcnt lgkmcnt(0)
	v_add_f32_e32 v16, v16, v17
	ds_bpermute_b32 v17, v192, v16
	v_cvt_pk_bf16_f32 v18, v20, v21
	v_cvt_pk_bf16_f32 v19, v22, v23
	v_cvt_pk_bf16_f32 v20, v28, v29
	v_cvt_pk_bf16_f32 v21, v30, v31
	global_store_dwordx4 v[32:33], v[24:27], off
	global_store_dwordx4 v[32:33], v[18:21], off offset:256
	s_and_saveexec_b64 s[6:7], s[38:39]
	s_cbranch_execz .LBB0_645
	s_waitcnt lgkmcnt(0)
	v_add_f32_e32 v16, v16, v17
	ds_write_b32 v176, v16 offset:640
.LBB0_645:
	s_or_b64 exec, exec, s[6:7]
	s_nop 0
	v_lshlrev_b32_e32 v18, 16, v68
	v_and_b32_e32 v19, 0xffff0000, v68
	v_lshlrev_b32_e32 v20, 16, v69
	v_and_b32_e32 v21, 0xffff0000, v69
	v_pk_add_f32 v[14:15], v[14:15], v[20:21]
	v_pk_add_f32 v[12:13], v[12:13], v[18:19]
	v_lshlrev_b32_e32 v18, 16, v70
	v_and_b32_e32 v19, 0xffff0000, v70
	v_lshlrev_b32_e32 v20, 16, v71
	v_and_b32_e32 v21, 0xffff0000, v71
	v_pk_add_f32 v[20:21], v[10:11], v[20:21]
	v_pk_add_f32 v[10:11], v[8:9], v[18:19]
	v_mul_f32_e32 v8, v13, v13
	v_mul_f32_e32 v9, v15, v15
	v_fmac_f32_e32 v8, v12, v12
	v_fmac_f32_e32 v9, v14, v14
	v_add_f32_e32 v8, v8, v9
	v_mul_f32_e32 v9, v11, v11
	v_mul_f32_e32 v18, v21, v21
	v_fmac_f32_e32 v9, v10, v10
	v_fmac_f32_e32 v18, v20, v20
	v_add_f32_e32 v9, v9, v18
	v_add_f32_e32 v18, v8, v9
	v_cvt_pk_bf16_f32 v8, v12, v13
	v_cvt_pk_bf16_f32 v9, v14, v15
	s_nop 0
	v_lshlrev_b32_e32 v12, 16, v64
	v_and_b32_e32 v13, 0xffff0000, v64
	v_lshlrev_b32_e32 v14, 16, v65
	v_and_b32_e32 v15, 0xffff0000, v65
	v_pk_add_f32 v[6:7], v[6:7], v[14:15]
	v_pk_add_f32 v[4:5], v[4:5], v[12:13]
	v_lshlrev_b32_e32 v12, 16, v66
	v_and_b32_e32 v13, 0xffff0000, v66
	v_lshlrev_b32_e32 v14, 16, v67
	v_and_b32_e32 v15, 0xffff0000, v67
	v_pk_add_f32 v[12:13], v[0:1], v[12:13]
	v_mul_f32_e32 v0, v5, v5
	v_mul_f32_e32 v1, v7, v7
	v_pk_add_f32 v[14:15], v[2:3], v[14:15]
	v_fmac_f32_e32 v0, v4, v4
	v_fmac_f32_e32 v1, v6, v6
	v_add_f32_e32 v0, v0, v1
	v_mul_f32_e32 v1, v13, v13
	v_mul_f32_e32 v2, v15, v15
	v_fmac_f32_e32 v1, v12, v12
	v_fmac_f32_e32 v2, v14, v14
	v_add_f32_e32 v1, v1, v2
	v_add_f32_e32 v0, v0, v1
	v_add_f32_e32 v0, v18, v0
	ds_bpermute_b32 v1, v193, v0
	s_waitcnt lgkmcnt(1)
	v_lshl_add_u64 v[16:17], s[84:85], 0, v[92:93]
	v_lshl_add_u64 v[16:17], v[164:165], 1, v[16:17]
	v_cvt_pk_bf16_f32 v10, v10, v11
	v_cvt_pk_bf16_f32 v11, v20, v21
	s_waitcnt lgkmcnt(0)
	v_add_f32_e32 v0, v0, v1
	ds_bpermute_b32 v1, v192, v0
	v_cvt_pk_bf16_f32 v2, v4, v5
	v_cvt_pk_bf16_f32 v3, v6, v7
	v_cvt_pk_bf16_f32 v4, v12, v13
	v_cvt_pk_bf16_f32 v5, v14, v15
	global_store_dwordx4 v[16:17], v[8:11], off
	global_store_dwordx4 v[16:17], v[2:5], off offset:256
	s_and_saveexec_b64 s[6:7], s[38:39]
	s_cbranch_execz .LBB0_647
	s_waitcnt lgkmcnt(0)
	v_add_f32_e32 v0, v0, v1
	ds_write_b32 v176, v0 offset:704
